# grid barrier flattened: no top-level counter; each XCD's last arriver writes back L2 and bumps all per-XCD generation words, everyone polls its own word for nx bumps
# speedup vs baseline: 1.0664x; 1.0078x over previous
.LBB0_1515:
	s_or_b64 exec, exec, s[4:5]
	v_cvt_f32_u32_e32 v4, v2
	s_waitcnt vmcnt(0)
	v_readfirstlane_b32 s4, v3
	v_sub_u32_e32 v3, 0, v2
	v_rcp_iflag_f32_e32 v4, v4
	v_add_u32_e32 v5, s4, v1
	v_mul_f32_e32 v4, 0x4f7ffffe, v4
	v_cvt_u32_f32_e32 v4, v4
	v_mul_lo_u32 v1, v3, v4
	v_mul_hi_u32 v1, v4, v1
	v_add_u32_e32 v1, v4, v1
	v_mul_hi_u32 v1, v5, v1
	v_mul_lo_u32 v3, v1, v2
	v_sub_u32_e32 v3, v5, v3
	v_add_u32_e32 v4, 1, v1
	v_cmp_ge_u32_e32 vcc, v3, v2
	s_nop 1
	v_cndmask_b32_e32 v1, v1, v4, vcc
	v_sub_u32_e32 v4, v3, v2
	v_cndmask_b32_e32 v3, v3, v4, vcc
	v_add_u32_e32 v4, 1, v1
	v_cmp_ge_u32_e32 vcc, v3, v2
	v_add_u32_e32 v3, 1, v5
	s_nop 0
	v_cndmask_b32_e32 v1, v1, v4, vcc
	v_mul_lo_u32 v4, v2, v1
	v_add_u32_e32 v2, v4, v2
	v_cmp_ne_u32_e32 vcc, v3, v2
	s_waitcnt lgkmcnt(0)
	v_add_u32_e32 v6, 1, v1
	v_mul_lo_u32 v6, v6, v0
	s_cbranch_vccnz .Lnb_poll
	buffer_wbl2 sc1
	s_waitcnt vmcnt(0)
	s_add_u32 s28, s52, 0x2400
	s_addc_u32 s29, s53, 0
	global_atomic_add v145, v161, s[28:29]
	global_atomic_add v145, v161, s[28:29] offset:256
	global_atomic_add v145, v161, s[28:29] offset:512
	global_atomic_add v145, v161, s[28:29] offset:768
	global_atomic_add v145, v161, s[28:29] offset:1024
	global_atomic_add v145, v161, s[28:29] offset:1280
	global_atomic_add v145, v161, s[28:29] offset:1536
	global_atomic_add v145, v161, s[28:29] offset:1792
	global_atomic_add v145, v161, s[28:29] offset:2048
	global_atomic_add v145, v161, s[28:29] offset:2304
	global_atomic_add v145, v161, s[28:29] offset:2560
	global_atomic_add v145, v161, s[28:29] offset:2816
	global_atomic_add v145, v161, s[28:29] offset:3072
	global_atomic_add v145, v161, s[28:29] offset:3328
	global_atomic_add v145, v161, s[28:29] offset:3584
	global_atomic_add v145, v161, s[28:29] offset:3840
.Lnb_poll:
	buffer_inv sc1
	v_readlane_b32 s24, v254, 51
	v_readlane_b32 s25, v254, 52
	s_mov_b32 s33, 0
	s_nop 4
.Lnb_loop:
	global_load_dword v7, v145, s[24:25] sc1
	s_waitcnt vmcnt(0)
	v_cmp_lt_u32_e32 vcc, v7, v6
	s_cbranch_vccz .Lnb_done
	s_sleep 1
	s_add_i32 s33, s33, 1
	s_cmp_lt_u32 s33, 0x400000
	s_cbranch_scc1 .Lnb_loop
.Lnb_done:
	s_waitcnt vmcnt(0)
	s_getpc_b64 s[98:99]
